# census loads of first grid barrier issued back-to-back with one wait
# baseline (speedup 1.0000x reference)
; __device__ __forceinline__ unsigned xb_ld(unsigned* p)              { return __hip_atomic_load(p, __ATOMIC_RELAXED, __HIP_MEMORY_SCOPE_AGENT); }
; __device__ __forceinline__ void xcd_barrier_complete(unsigned* bar, unsigned x, unsigned& nloc, unsigned& nx) {
;     ...
;     for (;;) {
;         sum = 0u; cnt = 0u; mine = 0u;
; #pragma unroll
;         for (unsigned j = 0; j < 16; ++j) { const unsigned c = xb_ld(&bar[XB_XCNT(j)]); sum += c; cnt += (c > 0u) ? 1u : 0u; mine = (j == x) ? c : mine; }
;         if (sum == G) break;
;         __builtin_amdgcn_s_sleep(1);
;         if ((++sp & 255u) == 0u) { if (xb_ld(&bar[XB_TMO])) break; if (sp > XB_SPIN_CAP) { atomicAdd(&bar[XB_TMO], 1u); break; } }
;     }
.LBB0_14:
	s_mov_b64 s[36:37], -1
	v_readlane_b32 s4, v251, 22
	v_readlane_b32 s5, v251, 23
	s_nop 4
	global_load_dword v2, v207, s[4:5] sc1
	v_readlane_b32 s4, v251, 24
	v_readlane_b32 s5, v251, 25
	s_nop 4
	global_load_dword v3, v207, s[4:5] sc1
	v_readlane_b32 s4, v251, 26
	v_readlane_b32 s5, v251, 27
	s_nop 4
	global_load_dword v4, v207, s[4:5] sc1
	v_readlane_b32 s4, v251, 28
	v_readlane_b32 s5, v251, 29
	s_nop 4
	global_load_dword v5, v207, s[4:5] sc1
	v_readlane_b32 s4, v251, 30
	v_readlane_b32 s5, v251, 31
	s_nop 4
	global_load_dword v6, v207, s[4:5] sc1
	v_readlane_b32 s4, v251, 32
	v_readlane_b32 s5, v251, 33
	s_nop 4
	global_load_dword v7, v207, s[4:5] sc1
	v_readlane_b32 s4, v251, 34
	v_readlane_b32 s5, v251, 35
	s_nop 4
	global_load_dword v8, v207, s[4:5] sc1
	v_readlane_b32 s4, v251, 36
	v_readlane_b32 s5, v251, 37
	s_nop 4
	global_load_dword v9, v207, s[4:5] sc1
	v_readlane_b32 s4, v251, 38
	v_readlane_b32 s5, v251, 39
	s_nop 4
	global_load_dword v10, v207, s[4:5] sc1
	v_readlane_b32 s4, v251, 40
	v_readlane_b32 s5, v251, 41
	s_nop 4
	global_load_dword v11, v207, s[4:5] sc1
	v_readlane_b32 s4, v251, 42
	v_readlane_b32 s5, v251, 43
	s_nop 4
	global_load_dword v12, v207, s[4:5] sc1
	v_readlane_b32 s4, v251, 44
	v_readlane_b32 s5, v251, 45
	s_nop 4
	global_load_dword v13, v207, s[4:5] sc1
	v_readlane_b32 s4, v251, 46
	v_readlane_b32 s5, v251, 47
	s_nop 4
	global_load_dword v14, v207, s[4:5] sc1
	v_readlane_b32 s4, v251, 48
	v_readlane_b32 s5, v251, 49
	s_nop 4
	global_load_dword v15, v207, s[4:5] sc1
	v_readlane_b32 s4, v251, 50
	v_readlane_b32 s5, v251, 51
	s_nop 4
	global_load_dword v16, v207, s[4:5] sc1
	v_readlane_b32 s4, v251, 52
	v_readlane_b32 s5, v251, 53
	s_nop 4
	global_load_dword v17, v207, s[4:5] sc1
	s_mov_b64 s[4:5], -1
	s_waitcnt vmcnt(0)
	v_add_u32_e32 v18, v3, v2
	v_add_u32_e32 v18, v18, v4
	v_add_u32_e32 v18, v18, v5
	v_add_u32_e32 v18, v18, v6
	v_add_u32_e32 v18, v18, v7
	v_add_u32_e32 v18, v18, v8
	v_add_u32_e32 v18, v18, v9
	v_add_u32_e32 v18, v18, v10
	v_add_u32_e32 v18, v18, v11
	v_add_u32_e32 v18, v18, v12
	v_add_u32_e32 v18, v18, v13
	v_add_u32_e32 v18, v18, v14
	v_add_u32_e32 v18, v18, v15
	v_add_u32_e32 v18, v18, v16
	v_add_u32_e32 v18, v18, v17
	v_cmp_eq_u32_e32 vcc, s34, v18
	s_cbranch_vccnz .LBB0_13
	s_and_b32 s4, s35, 0xff
	s_cmp_eq_u32 s4, 0
	s_mov_b64 s[4:5], -1
	s_mov_b64 s[38:39], -1
	s_sleep 1
	s_cbranch_scc1 .LBB0_18
	s_and_b64 vcc, exec, s[38:39]
	s_cbranch_vccz .LBB0_13
